# group barrier: last arriver (old%32==31) skips the poll loop and goes straight to buffer_inv; on top of v37
# baseline (speedup 1.0000x reference)
.LBB0_1102:
	s_or_b64 exec, exec, s[2:3]
	s_waitcnt vmcnt(0)
	v_readfirstlane_b32 s2, v1
	s_mov_b32 s18, 0x400001
	s_nop 0
	v_add_u32_e32 v0, s2, v0
	v_and_b32_e32 v0, 0xffffffe0, v0
	v_add_u32_e32 v0, 32, v0
	s_and_b32 s3, s2, 31
	s_cmp_eq_u32 s3, 31
	s_cbranch_scc1 .Lgb_last_arriver
	s_mov_b64 s[2:3], 0
	s_branch .LBB0_1108

.Lgb_last_arriver:
	buffer_inv sc1
	s_waitcnt vmcnt(0)
